# stack + final-phase panel-counter poll interval s_sleep 2 -> 1 (5 sites)
# baseline (speedup 1.0000x reference)
;     DI void operator()(Acc& acc, const Unit& u, int wr, int wc, int fr, int fq) const {
;     ...
;         if (wr == 0 && wc == 0 && fr == 0 && fq == 0) {
;             unsigned* cp = pcnt + 16 * u.pm;
;             __hip_atomic_fetch_add(cp, 1u, __ATOMIC_RELAXED, __HIP_MEMORY_SCOPE_AGENT);
;             unsigned sp = 0;
;             while (__hip_atomic_load(cp, __ATOMIC_RELAXED, __HIP_MEMORY_SCOPE_AGENT) < 4u) { __builtin_amdgcn_s_sleep(2); if (++sp > (1u << 22)) break; }
;             __builtin_amdgcn_fence(__ATOMIC_ACQUIRE, "agent");
;         }
.LBB0_1550:
	global_load_dword v2, v179, s[24:25] sc1
	s_mov_b64 s[26:27], -1
	s_waitcnt vmcnt(0)
	v_cmp_lt_u32_e32 vcc, 3, v2
	s_cbranch_vccnz .LBB0_1549
	s_sleep 1
	global_load_dword v2, v179, s[24:25] sc1
	s_waitcnt vmcnt(0)
	v_cmp_gt_u32_e32 vcc, 4, v2
	s_cbranch_vccz .LBB0_1549
	s_sleep 1
	global_load_dword v2, v179, s[24:25] sc1
	s_waitcnt vmcnt(0)
	v_cmp_gt_u32_e32 vcc, 4, v2
	s_cbranch_vccz .LBB0_1549
	s_sleep 1
	global_load_dword v2, v179, s[24:25] sc1
	s_waitcnt vmcnt(0)
	v_cmp_gt_u32_e32 vcc, 4, v2
	s_cbranch_vccz .LBB0_1549
	s_sleep 1
	global_load_dword v2, v179, s[24:25] sc1
	s_waitcnt vmcnt(0)
	v_cmp_gt_u32_e32 vcc, 4, v2
	s_cbranch_vccz .LBB0_1549
	s_add_i32 s28, s28, -5
	s_cmp_eq_u32 s28, 0
	s_cselect_b64 s[26:27], -1, 0
	s_sleep 1
	s_branch .LBB0_1549
